# carry phase publishes a counter instead of closing with a grid barrier; final-scan queue acquires it once
# speedup vs baseline: 1.0453x; 1.0161x over previous
; __global__ void __launch_bounds__(256, 2) hymba_forward(Params p) {
;     ...
;     carry_phase(p, layer);
;     xcd_barrier(xb);
.LBB0_1198:
	s_waitcnt vmcnt(0)
	s_barrier
	s_and_saveexec_b64 s[0:1], s[42:43]
	s_branch .LBB0_1252
	s_waitcnt vmcnt(0) expcnt(0) lgkmcnt(0)
	ds_read_b32 v3, v1
	ds_read_b32 v2, v1 offset:4
	s_waitcnt lgkmcnt(1)
	v_cmp_ne_u32_e32 vcc, 0, v3
	s_cbranch_vccnz .LBB0_1220
	s_mov_b32 s5, 1
	s_branch .LBB0_1208
.Lmy_carry_done:
	s_waitcnt vmcnt(0)
	s_barrier
	s_and_saveexec_b64 s[0:1], s[42:43]
	s_cbranch_execz .Lmy_carry_pub
	buffer_wbl2 sc1
	s_waitcnt vmcnt(0)
	v_readlane_b32 s100, v230, 2
	v_readlane_b32 s101, v230, 3
	v_readlane_b32 s5, v228, 28
	s_lshl_b32 s5, s5, 2
	s_add_u32 s100, s100, s5
	s_addc_u32 s101, s101, 0
	v_mov_b32_e32 v2, 1
	s_nop 4
	global_atomic_add v1, v2, s[100:101] offset:192
.Lmy_carry_pub:
	s_or_b64 exec, exec, s[0:1]
	s_branch .LBB0_1198

; __global__ void __launch_bounds__(256, 2) hymba_forward(Params p) {
;     ...
;       unsigned* ctr = p.ctr + layer * 2 + 1;
;       for (;;) {
;         const int it = next_item(ctr, sh_item);
;         if (it >= 1024 + 4096 + 2048) break;
;         if (it < 1024) lru_item<true>(p, layer, it, lds);
;         else if (it < 5120) s5_item<true>(p, layer, it - 1024, lds);
;         else mem_attn_item(p, layer, it - 5120, lds);
;       }
.LBB0_1281:
	s_and_saveexec_b64 s[0:1], s[42:43]
	s_cbranch_execz .Lmy_acq_done
	v_readlane_b32 s100, v230, 2
	v_readlane_b32 s101, v230, 3
	v_readlane_b32 s6, v228, 28
	s_lshl_b32 s6, s6, 2
	s_add_u32 s100, s100, s6
	s_addc_u32 s101, s101, 0
	s_nop 4
.Lmy_acq_spin:
	global_load_dword v2, v1, s[100:101] offset:192 sc1
	s_waitcnt vmcnt(0)
	v_readfirstlane_b32 s6, v2
	s_cmp_ge_u32 s6, 40
	s_cbranch_scc1 .Lmy_acq_ok
	s_sleep 8
	s_branch .Lmy_acq_spin
.Lmy_acq_ok:
	buffer_inv sc1
	s_waitcnt vmcnt(0)
.Lmy_acq_done:
	s_or_b64 exec, exec, s[0:1]
	s_barrier
	v_readlane_b32 s6, v228, 28
	s_lshl_b32 s0, s6, 20
	s_add_u32 s26, s62, s0
	s_addc_u32 s27, s63, 0
	s_lshl_b32 s28, s6, 4
	v_readlane_b32 s7, v228, 29
	s_branch .LBB0_1284
